# attention softmax: single v_max for the row-max head instead of two canonicalising max plus combine
# speedup vs baseline: 1.0017x; 1.0017x over previous
.LBB0_110:
	s_nop 10
	v_max_f32_e32 v214, v64, v65
	v_max3_f32 v214, v214, v66, v67
	v_max3_f32 v214, v214, v68, v69
	v_max3_f32 v214, v214, v70, v71
	v_max3_f32 v214, v214, v72, v73
	v_xor_b32_e32 v215, 32, v208
	v_max3_f32 v214, v214, v74, v75
	v_max3_f32 v214, v214, v76, v77
	v_max3_f32 v214, v214, v78, v79
	v_lshlrev_b32_e32 v230, 2, v215
	ds_bpermute_b32 v215, v230, v214
	s_waitcnt lgkmcnt(0)
	v_max3_f32 v234, v228, v214, v215
	v_sub_f32_e32 v64, v64, v234
	v_exp_f32_e32 v235, v64
	v_sub_f32_e32 v65, v65, v234
	v_exp_f32_e32 v65, v65
	v_sub_f32_e32 v66, v66, v234
	v_exp_f32_e32 v66, v66
	v_sub_f32_e32 v67, v67, v234
	v_exp_f32_e32 v67, v67
	v_sub_f32_e32 v68, v68, v234
	v_add_f32_e32 v214, 0, v235
	v_exp_f32_e32 v68, v68
	v_sub_f32_e32 v69, v69, v234
	v_sub_f32_e32 v64, v228, v234
	v_add_f32_e32 v214, v65, v214
	v_exp_f32_e32 v228, v69
	v_sub_f32_e32 v69, v70, v234
	v_add_f32_e32 v214, v66, v214
	v_exp_f32_e32 v236, v69
	v_sub_f32_e32 v69, v71, v234
	v_add_f32_e32 v214, v67, v214
	v_exp_f32_e32 v237, v69
	v_sub_f32_e32 v69, v72, v234
	v_add_f32_e32 v214, v68, v214
	v_exp_f32_e32 v69, v69
	v_add_f32_e32 v70, v228, v214
	v_add_f32_e32 v70, v236, v70
	v_add_f32_e32 v70, v237, v70
	v_add_f32_e32 v214, v69, v70
	v_sub_f32_e32 v70, v73, v234
	v_exp_f32_e32 v70, v70
	v_sub_f32_e32 v71, v74, v234
	v_exp_f32_e32 v71, v71
	v_sub_f32_e32 v72, v75, v234
	v_exp_f32_e32 v72, v72
	v_sub_f32_e32 v73, v76, v234
	v_exp_f32_e32 v73, v73
	v_add_f32_e32 v74, v70, v214
	v_add_f32_e32 v74, v71, v74
	v_add_f32_e32 v74, v72, v74
	v_add_f32_e32 v214, v73, v74
	v_sub_f32_e32 v74, v77, v234
	v_exp_f32_e32 v74, v74
	v_sub_f32_e32 v75, v78, v234
	v_exp_f32_e32 v75, v75
	v_sub_f32_e32 v76, v79, v234
	v_exp_f32_e32 v76, v76
	v_add_f32_e32 v77, v74, v214
	v_add_f32_e32 v77, v75, v77
	v_exp_f32_e32 v64, v64
	v_add_f32_e32 v77, v76, v77
	ds_bpermute_b32 v78, v230, v77
	v_cmp_neq_f32_e32 vcc, 1.0, v64
	s_cbranch_vccz .LBB0_112
	v_pk_mul_f32 v[62:63], v[62:63], v[64:65] op_sel_hi:[1,0]
	v_pk_mul_f32 v[60:61], v[60:61], v[64:65] op_sel_hi:[1,0]
	v_pk_mul_f32 v[58:59], v[58:59], v[64:65] op_sel_hi:[1,0]
	v_pk_mul_f32 v[56:57], v[56:57], v[64:65] op_sel_hi:[1,0]
	v_pk_mul_f32 v[54:55], v[54:55], v[64:65] op_sel_hi:[1,0]
	v_pk_mul_f32 v[52:53], v[52:53], v[64:65] op_sel_hi:[1,0]
	v_pk_mul_f32 v[50:51], v[50:51], v[64:65] op_sel_hi:[1,0]
	v_pk_mul_f32 v[48:49], v[48:49], v[64:65] op_sel_hi:[1,0]
	v_pk_mul_f32 v[46:47], v[46:47], v[64:65] op_sel_hi:[1,0]
	v_pk_mul_f32 v[44:45], v[44:45], v[64:65] op_sel_hi:[1,0]
	v_pk_mul_f32 v[42:43], v[42:43], v[64:65] op_sel_hi:[1,0]
	v_pk_mul_f32 v[40:41], v[40:41], v[64:65] op_sel_hi:[1,0]
	v_pk_mul_f32 v[38:39], v[38:39], v[64:65] op_sel_hi:[1,0]
	v_pk_mul_f32 v[36:37], v[36:37], v[64:65] op_sel_hi:[1,0]
	v_pk_mul_f32 v[34:35], v[34:35], v[64:65] op_sel_hi:[1,0]
	v_pk_mul_f32 v[32:33], v[32:33], v[64:65] op_sel_hi:[1,0]
	v_pk_mul_f32 v[30:31], v[30:31], v[64:65] op_sel_hi:[1,0]
	v_pk_mul_f32 v[28:29], v[28:29], v[64:65] op_sel_hi:[1,0]
	v_pk_mul_f32 v[26:27], v[26:27], v[64:65] op_sel_hi:[1,0]
	v_pk_mul_f32 v[24:25], v[24:25], v[64:65] op_sel_hi:[1,0]
	v_pk_mul_f32 v[22:23], v[22:23], v[64:65] op_sel_hi:[1,0]
	v_pk_mul_f32 v[20:21], v[20:21], v[64:65] op_sel_hi:[1,0]
	v_pk_mul_f32 v[18:19], v[18:19], v[64:65] op_sel_hi:[1,0]
	v_pk_mul_f32 v[16:17], v[16:17], v[64:65] op_sel_hi:[1,0]
	v_pk_mul_f32 v[14:15], v[14:15], v[64:65] op_sel_hi:[1,0]
	v_pk_mul_f32 v[12:13], v[12:13], v[64:65] op_sel_hi:[1,0]
	v_pk_mul_f32 v[10:11], v[10:11], v[64:65] op_sel_hi:[1,0]
	v_pk_mul_f32 v[8:9], v[8:9], v[64:65] op_sel_hi:[1,0]
	v_pk_mul_f32 v[6:7], v[6:7], v[64:65] op_sel_hi:[1,0]
	v_pk_mul_f32 v[4:5], v[4:5], v[64:65] op_sel_hi:[1,0]
	v_pk_mul_f32 v[2:3], v[2:3], v[64:65] op_sel_hi:[1,0]
	v_pk_mul_f32 v[0:1], v[0:1], v[64:65] op_sel_hi:[1,0]

.LBB0_115:
	s_nop 10
	v_max_f32_e32 v214, v64, v65
	v_max3_f32 v214, v214, v66, v67
	v_max3_f32 v214, v214, v68, v69
	v_max3_f32 v214, v214, v70, v71
	v_max3_f32 v214, v214, v72, v73
	v_max3_f32 v214, v214, v74, v75
	v_max3_f32 v214, v214, v76, v77
	v_max3_f32 v214, v214, v78, v79
	ds_bpermute_b32 v215, v230, v214
	s_waitcnt lgkmcnt(0)
	v_max3_f32 v228, v234, v214, v215
	v_sub_f32_e32 v64, v64, v228
	v_sub_f32_e32 v215, v65, v228
	v_exp_f32_e32 v65, v64
	v_sub_f32_e32 v216, v66, v228
	v_exp_f32_e32 v66, v215
	v_sub_f32_e32 v64, v67, v228
	v_exp_f32_e32 v67, v216
	v_exp_f32_e32 v229, v64
	v_sub_f32_e32 v64, v68, v228
	v_add_f32_e32 v215, 0, v65
	v_exp_f32_e32 v68, v64
	v_sub_f32_e32 v69, v69, v228
	v_add_f32_e32 v64, v66, v215
	v_exp_f32_e32 v231, v69
	v_sub_f32_e32 v69, v70, v228
	v_add_f32_e32 v64, v67, v64
	v_exp_f32_e32 v233, v69
	v_sub_f32_e32 v69, v71, v228
	v_sub_f32_e32 v214, v234, v228
	v_add_f32_e32 v64, v229, v64
	v_exp_f32_e32 v234, v69
	v_sub_f32_e32 v69, v72, v228
	v_add_f32_e32 v64, v68, v64
	v_exp_f32_e32 v69, v69
	v_sub_f32_e32 v70, v73, v228
	v_add_f32_e32 v64, v231, v64
	v_exp_f32_e32 v70, v70
	v_sub_f32_e32 v71, v74, v228
	v_add_f32_e32 v64, v233, v64
	v_exp_f32_e32 v71, v71
	v_sub_f32_e32 v72, v75, v228
	v_add_f32_e32 v64, v234, v64
	v_exp_f32_e32 v72, v72
	v_sub_f32_e32 v73, v76, v228
	v_add_f32_e32 v64, v69, v64
	v_exp_f32_e32 v73, v73
	v_sub_f32_e32 v74, v77, v228
	v_add_f32_e32 v64, v70, v64
	v_exp_f32_e32 v74, v74
	v_sub_f32_e32 v75, v78, v228
	v_add_f32_e32 v64, v71, v64
	v_exp_f32_e32 v75, v75
	v_sub_f32_e32 v76, v79, v228
	v_add_f32_e32 v64, v72, v64
	v_exp_f32_e32 v76, v76
	v_add_f32_e32 v64, v73, v64
	v_add_f32_e32 v64, v74, v64
	v_add_f32_e32 v77, v75, v64
	v_add_f32_e32 v77, v76, v77
	v_exp_f32_e32 v64, v214
	ds_bpermute_b32 v78, v230, v77
	v_cmp_neq_f32_e32 vcc, 1.0, v64
	s_cbranch_vccz .LBB0_117
	v_pk_mul_f32 v[62:63], v[62:63], v[64:65] op_sel_hi:[1,0]
	v_pk_mul_f32 v[60:61], v[60:61], v[64:65] op_sel_hi:[1,0]
	v_pk_mul_f32 v[58:59], v[58:59], v[64:65] op_sel_hi:[1,0]
	v_pk_mul_f32 v[56:57], v[56:57], v[64:65] op_sel_hi:[1,0]
	v_pk_mul_f32 v[54:55], v[54:55], v[64:65] op_sel_hi:[1,0]
	v_pk_mul_f32 v[52:53], v[52:53], v[64:65] op_sel_hi:[1,0]
	v_pk_mul_f32 v[50:51], v[50:51], v[64:65] op_sel_hi:[1,0]
	v_pk_mul_f32 v[48:49], v[48:49], v[64:65] op_sel_hi:[1,0]
	v_pk_mul_f32 v[46:47], v[46:47], v[64:65] op_sel_hi:[1,0]
	v_pk_mul_f32 v[44:45], v[44:45], v[64:65] op_sel_hi:[1,0]
	v_pk_mul_f32 v[42:43], v[42:43], v[64:65] op_sel_hi:[1,0]
	v_pk_mul_f32 v[40:41], v[40:41], v[64:65] op_sel_hi:[1,0]
	v_pk_mul_f32 v[38:39], v[38:39], v[64:65] op_sel_hi:[1,0]
	v_pk_mul_f32 v[36:37], v[36:37], v[64:65] op_sel_hi:[1,0]
	v_pk_mul_f32 v[34:35], v[34:35], v[64:65] op_sel_hi:[1,0]
	v_pk_mul_f32 v[32:33], v[32:33], v[64:65] op_sel_hi:[1,0]
	v_pk_mul_f32 v[30:31], v[30:31], v[64:65] op_sel_hi:[1,0]
	v_pk_mul_f32 v[28:29], v[28:29], v[64:65] op_sel_hi:[1,0]
	v_pk_mul_f32 v[26:27], v[26:27], v[64:65] op_sel_hi:[1,0]
	v_pk_mul_f32 v[24:25], v[24:25], v[64:65] op_sel_hi:[1,0]
	v_pk_mul_f32 v[22:23], v[22:23], v[64:65] op_sel_hi:[1,0]
	v_pk_mul_f32 v[20:21], v[20:21], v[64:65] op_sel_hi:[1,0]
	v_pk_mul_f32 v[18:19], v[18:19], v[64:65] op_sel_hi:[1,0]
	v_pk_mul_f32 v[16:17], v[16:17], v[64:65] op_sel_hi:[1,0]
	v_pk_mul_f32 v[14:15], v[14:15], v[64:65] op_sel_hi:[1,0]
	v_pk_mul_f32 v[12:13], v[12:13], v[64:65] op_sel_hi:[1,0]
	v_pk_mul_f32 v[10:11], v[10:11], v[64:65] op_sel_hi:[1,0]
	v_pk_mul_f32 v[8:9], v[8:9], v[64:65] op_sel_hi:[1,0]
	v_pk_mul_f32 v[6:7], v[6:7], v[64:65] op_sel_hi:[1,0]
	v_pk_mul_f32 v[4:5], v[4:5], v[64:65] op_sel_hi:[1,0]
	v_pk_mul_f32 v[2:3], v[2:3], v[64:65] op_sel_hi:[1,0]
	v_pk_mul_f32 v[0:1], v[0:1], v[64:65] op_sel_hi:[1,0]

.LBB0_149:
	s_nop 10
	v_max_f32_e32 v214, v64, v65
	v_max3_f32 v214, v214, v66, v67
	v_max3_f32 v214, v214, v68, v69
	v_max3_f32 v214, v214, v70, v71
	v_max3_f32 v214, v214, v72, v73
	v_xor_b32_e32 v215, 32, v208
	v_max3_f32 v214, v214, v74, v75
	v_max3_f32 v214, v214, v76, v77
	v_max3_f32 v214, v214, v78, v79
	v_lshlrev_b32_e32 v238, 2, v215
	ds_bpermute_b32 v215, v238, v214
	v_mov_b32_e32 v248, v218
	s_waitcnt lgkmcnt(0)
	v_max3_f32 v242, v236, v214, v215
	v_sub_f32_e32 v64, v64, v242
	v_exp_f32_e32 v243, v64
	v_sub_f32_e32 v65, v65, v242
	v_exp_f32_e32 v65, v65
	v_sub_f32_e32 v66, v66, v242
	v_exp_f32_e32 v66, v66
	v_sub_f32_e32 v67, v67, v242
	v_exp_f32_e32 v67, v67
	v_sub_f32_e32 v68, v68, v242
	v_add_f32_e32 v214, 0, v243
	v_exp_f32_e32 v68, v68
	v_sub_f32_e32 v69, v69, v242
	v_sub_f32_e32 v64, v236, v242
	v_add_f32_e32 v214, v65, v214
	v_exp_f32_e32 v236, v69
	v_sub_f32_e32 v69, v70, v242
	v_add_f32_e32 v214, v66, v214
	v_exp_f32_e32 v244, v69
	v_sub_f32_e32 v69, v71, v242
	v_add_f32_e32 v214, v67, v214
	v_exp_f32_e32 v245, v69
	v_sub_f32_e32 v69, v72, v242
	v_add_f32_e32 v214, v68, v214
	v_exp_f32_e32 v69, v69
	v_add_f32_e32 v70, v236, v214
	v_add_f32_e32 v70, v244, v70
	v_add_f32_e32 v70, v245, v70
	v_add_f32_e32 v214, v69, v70
	v_sub_f32_e32 v70, v73, v242
	v_exp_f32_e32 v70, v70
	v_sub_f32_e32 v71, v74, v242
	v_exp_f32_e32 v71, v71
	v_sub_f32_e32 v72, v75, v242
	v_exp_f32_e32 v72, v72
	v_sub_f32_e32 v73, v76, v242
	v_exp_f32_e32 v73, v73
	v_add_f32_e32 v74, v70, v214
	v_add_f32_e32 v74, v71, v74
	v_add_f32_e32 v74, v72, v74
	v_add_f32_e32 v214, v73, v74
	v_sub_f32_e32 v74, v77, v242
	v_exp_f32_e32 v74, v74
	v_sub_f32_e32 v75, v78, v242
	v_exp_f32_e32 v75, v75
	v_sub_f32_e32 v76, v79, v242
	v_exp_f32_e32 v76, v76
	v_add_f32_e32 v77, v74, v214
	v_add_f32_e32 v77, v75, v77
	v_exp_f32_e32 v64, v64
	v_add_f32_e32 v77, v76, v77
	ds_bpermute_b32 v78, v238, v77
	v_cmp_neq_f32_e32 vcc, 1.0, v64
	s_cbranch_vccz .LBB0_151
	v_pk_mul_f32 v[62:63], v[62:63], v[64:65] op_sel_hi:[1,0]
	v_pk_mul_f32 v[60:61], v[60:61], v[64:65] op_sel_hi:[1,0]
	v_pk_mul_f32 v[58:59], v[58:59], v[64:65] op_sel_hi:[1,0]
	v_pk_mul_f32 v[56:57], v[56:57], v[64:65] op_sel_hi:[1,0]
	v_pk_mul_f32 v[54:55], v[54:55], v[64:65] op_sel_hi:[1,0]
	v_pk_mul_f32 v[52:53], v[52:53], v[64:65] op_sel_hi:[1,0]
	v_pk_mul_f32 v[50:51], v[50:51], v[64:65] op_sel_hi:[1,0]
	v_pk_mul_f32 v[48:49], v[48:49], v[64:65] op_sel_hi:[1,0]
	v_pk_mul_f32 v[46:47], v[46:47], v[64:65] op_sel_hi:[1,0]
	v_pk_mul_f32 v[44:45], v[44:45], v[64:65] op_sel_hi:[1,0]
	v_pk_mul_f32 v[42:43], v[42:43], v[64:65] op_sel_hi:[1,0]
	v_pk_mul_f32 v[40:41], v[40:41], v[64:65] op_sel_hi:[1,0]
	v_pk_mul_f32 v[38:39], v[38:39], v[64:65] op_sel_hi:[1,0]
	v_pk_mul_f32 v[36:37], v[36:37], v[64:65] op_sel_hi:[1,0]
	v_pk_mul_f32 v[34:35], v[34:35], v[64:65] op_sel_hi:[1,0]
	v_pk_mul_f32 v[32:33], v[32:33], v[64:65] op_sel_hi:[1,0]
	v_pk_mul_f32 v[30:31], v[30:31], v[64:65] op_sel_hi:[1,0]
	v_pk_mul_f32 v[28:29], v[28:29], v[64:65] op_sel_hi:[1,0]
	v_pk_mul_f32 v[26:27], v[26:27], v[64:65] op_sel_hi:[1,0]
	v_pk_mul_f32 v[24:25], v[24:25], v[64:65] op_sel_hi:[1,0]
	v_pk_mul_f32 v[22:23], v[22:23], v[64:65] op_sel_hi:[1,0]
	v_pk_mul_f32 v[20:21], v[20:21], v[64:65] op_sel_hi:[1,0]
	v_pk_mul_f32 v[18:19], v[18:19], v[64:65] op_sel_hi:[1,0]
	v_pk_mul_f32 v[16:17], v[16:17], v[64:65] op_sel_hi:[1,0]
	v_pk_mul_f32 v[14:15], v[14:15], v[64:65] op_sel_hi:[1,0]
	v_pk_mul_f32 v[12:13], v[12:13], v[64:65] op_sel_hi:[1,0]
	v_pk_mul_f32 v[10:11], v[10:11], v[64:65] op_sel_hi:[1,0]
	v_pk_mul_f32 v[8:9], v[8:9], v[64:65] op_sel_hi:[1,0]
	v_pk_mul_f32 v[6:7], v[6:7], v[64:65] op_sel_hi:[1,0]
	v_pk_mul_f32 v[4:5], v[4:5], v[64:65] op_sel_hi:[1,0]
	v_pk_mul_f32 v[2:3], v[2:3], v[64:65] op_sel_hi:[1,0]
	v_pk_mul_f32 v[0:1], v[0:1], v[64:65] op_sel_hi:[1,0]

.LBB0_154:
	s_nop 10
	v_max_f32_e32 v214, v64, v65
	v_max3_f32 v214, v214, v66, v67
	v_max3_f32 v214, v214, v68, v69
	v_max3_f32 v214, v214, v70, v71
	v_max3_f32 v214, v214, v72, v73
	v_max3_f32 v214, v214, v74, v75
	v_max3_f32 v214, v214, v76, v77
	v_max3_f32 v214, v214, v78, v79
	ds_bpermute_b32 v215, v238, v214
	s_waitcnt lgkmcnt(0)
	v_max3_f32 v236, v242, v214, v215
	v_sub_f32_e32 v64, v64, v236
	v_sub_f32_e32 v215, v65, v236
	v_exp_f32_e32 v65, v64
	v_sub_f32_e32 v216, v66, v236
	v_exp_f32_e32 v66, v215
	v_sub_f32_e32 v64, v67, v236
	v_exp_f32_e32 v67, v216
	v_exp_f32_e32 v237, v64
	v_sub_f32_e32 v64, v68, v236
	v_add_f32_e32 v215, 0, v65
	v_exp_f32_e32 v68, v64
	v_sub_f32_e32 v69, v69, v236
	v_add_f32_e32 v64, v66, v215
	v_exp_f32_e32 v239, v69
	v_sub_f32_e32 v69, v70, v236
	v_add_f32_e32 v64, v67, v64
	v_exp_f32_e32 v241, v69
	v_sub_f32_e32 v69, v71, v236
	v_sub_f32_e32 v214, v242, v236
	v_add_f32_e32 v64, v237, v64
	v_exp_f32_e32 v242, v69
	v_sub_f32_e32 v69, v72, v236
	v_add_f32_e32 v64, v68, v64
	v_exp_f32_e32 v69, v69
	v_sub_f32_e32 v70, v73, v236
	v_add_f32_e32 v64, v239, v64
	v_exp_f32_e32 v70, v70
	v_sub_f32_e32 v71, v74, v236
	v_add_f32_e32 v64, v241, v64
	v_exp_f32_e32 v71, v71
	v_sub_f32_e32 v72, v75, v236
	v_add_f32_e32 v64, v242, v64
	v_exp_f32_e32 v72, v72
	v_sub_f32_e32 v73, v76, v236
	v_add_f32_e32 v64, v69, v64
	v_exp_f32_e32 v73, v73
	v_sub_f32_e32 v74, v77, v236
	v_add_f32_e32 v64, v70, v64
	v_exp_f32_e32 v74, v74
	v_sub_f32_e32 v75, v78, v236
	v_add_f32_e32 v64, v71, v64
	v_exp_f32_e32 v75, v75
	v_sub_f32_e32 v76, v79, v236
	v_add_f32_e32 v64, v72, v64
	v_exp_f32_e32 v76, v76
	v_add_f32_e32 v64, v73, v64
	v_add_f32_e32 v64, v74, v64
	v_add_f32_e32 v77, v75, v64
	v_add_f32_e32 v77, v76, v77
	v_exp_f32_e32 v64, v214
	ds_bpermute_b32 v78, v238, v77
	v_cmp_neq_f32_e32 vcc, 1.0, v64
	s_cbranch_vccz .LBB0_156
	v_pk_mul_f32 v[62:63], v[62:63], v[64:65] op_sel_hi:[1,0]
	v_pk_mul_f32 v[60:61], v[60:61], v[64:65] op_sel_hi:[1,0]
	v_pk_mul_f32 v[58:59], v[58:59], v[64:65] op_sel_hi:[1,0]
	v_pk_mul_f32 v[56:57], v[56:57], v[64:65] op_sel_hi:[1,0]
	v_pk_mul_f32 v[54:55], v[54:55], v[64:65] op_sel_hi:[1,0]
	v_pk_mul_f32 v[52:53], v[52:53], v[64:65] op_sel_hi:[1,0]
	v_pk_mul_f32 v[50:51], v[50:51], v[64:65] op_sel_hi:[1,0]
	v_pk_mul_f32 v[48:49], v[48:49], v[64:65] op_sel_hi:[1,0]
	v_pk_mul_f32 v[46:47], v[46:47], v[64:65] op_sel_hi:[1,0]
	v_pk_mul_f32 v[44:45], v[44:45], v[64:65] op_sel_hi:[1,0]
	v_pk_mul_f32 v[42:43], v[42:43], v[64:65] op_sel_hi:[1,0]
	v_pk_mul_f32 v[40:41], v[40:41], v[64:65] op_sel_hi:[1,0]
	v_pk_mul_f32 v[38:39], v[38:39], v[64:65] op_sel_hi:[1,0]
	v_pk_mul_f32 v[36:37], v[36:37], v[64:65] op_sel_hi:[1,0]
	v_pk_mul_f32 v[34:35], v[34:35], v[64:65] op_sel_hi:[1,0]
	v_pk_mul_f32 v[32:33], v[32:33], v[64:65] op_sel_hi:[1,0]
	v_pk_mul_f32 v[30:31], v[30:31], v[64:65] op_sel_hi:[1,0]
	v_pk_mul_f32 v[28:29], v[28:29], v[64:65] op_sel_hi:[1,0]
	v_pk_mul_f32 v[26:27], v[26:27], v[64:65] op_sel_hi:[1,0]
	v_pk_mul_f32 v[24:25], v[24:25], v[64:65] op_sel_hi:[1,0]
	v_pk_mul_f32 v[22:23], v[22:23], v[64:65] op_sel_hi:[1,0]
	v_pk_mul_f32 v[20:21], v[20:21], v[64:65] op_sel_hi:[1,0]
	v_pk_mul_f32 v[18:19], v[18:19], v[64:65] op_sel_hi:[1,0]
	v_pk_mul_f32 v[16:17], v[16:17], v[64:65] op_sel_hi:[1,0]
	v_pk_mul_f32 v[14:15], v[14:15], v[64:65] op_sel_hi:[1,0]
	v_pk_mul_f32 v[12:13], v[12:13], v[64:65] op_sel_hi:[1,0]
	v_pk_mul_f32 v[10:11], v[10:11], v[64:65] op_sel_hi:[1,0]
	v_pk_mul_f32 v[8:9], v[8:9], v[64:65] op_sel_hi:[1,0]
	v_pk_mul_f32 v[6:7], v[6:7], v[64:65] op_sel_hi:[1,0]
	v_pk_mul_f32 v[4:5], v[4:5], v[64:65] op_sel_hi:[1,0]
	v_pk_mul_f32 v[2:3], v[2:3], v[64:65] op_sel_hi:[1,0]
	v_pk_mul_f32 v[0:1], v[0:1], v[64:65] op_sel_hi:[1,0]
